# P1 gate epilogue: softplus and log-sigmoid lanes share one pass of the log1p(exp(-|x|)) routine (was two divergent branches executed back to back); per-lane select of bias array, max/min and add/sub
# baseline (speedup 1.0000x reference)
.LBB0_224:
	ds_read2st64_b32 v[2:3], v1 offset1:24
	ds_read2st64_b32 v[4:5], v1 offset0:48 offset1:72
	ds_read2st64_b32 v[6:7], v1 offset0:96 offset1:120
	ds_read2st64_b32 v[8:9], v1 offset0:144 offset1:168
	v_mul_hi_i32 v10, v0, s22
	s_waitcnt lgkmcnt(3)
	v_add_f32_e32 v2, 0, v2
	v_add_f32_e32 v2, v2, v3
	s_waitcnt lgkmcnt(2)
	v_add_f32_e32 v2, v2, v4
	v_add_f32_e32 v2, v2, v5
	s_waitcnt lgkmcnt(1)
	v_add_f32_e32 v2, v2, v6
	v_add_f32_e32 v2, v2, v7
	s_waitcnt lgkmcnt(0)
	v_add_f32_e32 v2, v2, v8
	v_add_f32_e32 v5, v2, v9
	v_lshrrev_b32_e32 v2, 31, v10
	v_ashrrev_i32_e32 v3, 3, v10
	v_add_u32_e32 v4, v3, v2
	v_mad_u64_u32 v[2:3], s[0:1], v4, s23, v[0:1]
	v_cmp_lt_i32_e64 s[0:1], 7, v2
	s_and_saveexec_b64 s[68:69], s[0:1]
	s_xor_b64 s[68:69], exec, s[68:69]
	s_cbranch_execz .LBB0_230
	v_cmp_lt_u32_e64 s[82:83], 15, v2
	v_mov_b32_e32 v3, v111
	v_readlane_b32 s36, v254, 26
	v_readlane_b32 s38, v254, 28
	v_readlane_b32 s39, v254, 29
	v_readlane_b32 s37, v254, 27
	v_readlane_b32 s40, v254, 30
	v_lshl_add_u64 v[6:7], v[2:3], 2, s[38:39]
	v_lshl_add_u64 v[20:21], v[2:3], 2, s[76:77]
	v_mov_b32_e32 v22, -32
	v_mov_b32_e32 v23, -64
	v_cndmask_b32_e64 v6, v20, v6, s[82:83]
	v_cndmask_b32_e64 v7, v21, v7, s[82:83]
	v_cndmask_b32_e64 v20, v22, v23, s[82:83]
	v_mov_b32_e32 v21, -1
	v_lshl_add_u64 v[6:7], v[6:7], 0, v[20:21]
	global_load_dword v3, v[6:7], off
	v_readlane_b32 s41, v254, 31
	v_readlane_b32 s42, v254, 32
	v_readlane_b32 s43, v254, 33
	v_readlane_b32 s44, v254, 34
	v_readlane_b32 s45, v254, 35
	v_readlane_b32 s46, v254, 36
	v_readlane_b32 s47, v254, 37
	v_readlane_b32 s48, v254, 38
	v_readlane_b32 s49, v254, 39
	v_readlane_b32 s50, v254, 40
	v_readlane_b32 s51, v254, 41
	s_waitcnt vmcnt(0)
	v_add_f32_e32 v5, v5, v3
	v_mul_f32_e64 v6, |v5|, s24
	v_fma_f32 v7, |v5|, s24, -v6
	v_rndne_f32_e32 v8, v6
	v_fma_f32 v7, |v5|, s25, v7
	v_sub_f32_e32 v6, v6, v8
	v_add_f32_e32 v6, v6, v7
	v_exp_f32_e32 v6, v6
	v_cvt_i32_f32_e32 v7, v8
	v_cmp_ngt_f32_e64 s[0:1], |v5|, s26
	v_min_f32_e32 v20, 0, v5
	v_max_f32_e32 v3, 0, v5
	v_cndmask_b32_e64 v3, v20, v3, s[82:83]
	v_ldexp_f32 v6, v6, v7
	v_cndmask_b32_e64 v6, 0, v6, s[0:1]
	v_cmp_nlt_f32_e64 s[0:1], |v5|, s27
	s_nop 1
	v_cndmask_b32_e64 v5, v197, v6, s[0:1]
	v_add_f32_e32 v8, 1.0, v5
	v_add_f32_e32 v6, -1.0, v8
	v_sub_f32_e32 v7, v6, v8
	v_add_f32_e32 v7, 1.0, v7
	v_sub_f32_e32 v6, v5, v6
	v_add_f32_e32 v9, v6, v7
	v_frexp_mant_f32_e32 v6, v8
	v_cmp_gt_f32_e64 s[0:1], s65, v6
	v_cvt_f64_f32_e32 v[6:7], v8
	v_frexp_exp_i32_f64_e32 v6, v[6:7]
	v_subbrev_co_u32_e64 v14, s[0:1], 0, v6, s[0:1]
	v_sub_u32_e32 v6, 0, v14
	v_ldexp_f32 v7, v8, v6
	v_add_f32_e32 v8, -1.0, v7
	v_add_f32_e32 v10, 1.0, v7
	v_ldexp_f32 v6, v9, v6
	v_add_f32_e32 v9, 1.0, v8
	v_add_f32_e32 v11, -1.0, v10
	v_sub_f32_e32 v9, v7, v9
	v_sub_f32_e32 v7, v7, v11
	v_add_f32_e32 v9, v6, v9
	v_add_f32_e32 v6, v6, v7
	v_add_f32_e32 v15, v10, v6
	v_rcp_f32_e32 v17, v15
	v_sub_f32_e32 v7, v10, v15
	v_add_f32_e32 v16, v6, v7
	v_add_f32_e32 v7, v8, v9
	v_mul_f32_e32 v19, v7, v17
	v_sub_f32_e32 v6, v8, v7
	v_mul_f32_e32 v8, v15, v19
	v_fma_f32 v10, v19, v15, -v8
	v_fmac_f32_e32 v10, v19, v16
	v_add_f32_e32 v18, v9, v6
	v_add_f32_e32 v6, v8, v10
	v_sub_f32_e32 v9, v7, v6
	v_pk_add_f32 v[12:13], v[6:7], v[8:9] neg_lo:[0,1] neg_hi:[0,1]
	v_mov_b32_e32 v11, v6
	v_pk_add_f32 v[6:7], v[12:13], v[10:11] neg_lo:[0,1] neg_hi:[0,1]
	v_cmp_neq_f32_e64 s[0:1], s64, v5
	v_add_f32_e32 v7, v18, v7
	v_add_f32_e32 v6, v6, v7
	v_add_f32_e32 v7, v9, v6
	v_mul_f32_e32 v18, v17, v7
	v_mul_f32_e32 v8, v15, v18
	v_fma_f32 v10, v18, v15, -v8
	v_fmac_f32_e32 v10, v18, v16
	v_sub_f32_e32 v9, v9, v7
	v_add_f32_e32 v15, v6, v9
	v_add_f32_e32 v6, v8, v10
	v_sub_f32_e32 v9, v7, v6
	v_pk_add_f32 v[12:13], v[6:7], v[8:9] neg_lo:[0,1] neg_hi:[0,1]
	v_mov_b32_e32 v11, v6
	v_pk_add_f32 v[6:7], v[12:13], v[10:11] neg_lo:[0,1] neg_hi:[0,1]
	s_nop 0
	v_add_f32_e32 v7, v15, v7
	v_add_f32_e32 v6, v6, v7
	v_add_f32_e32 v7, v19, v18
	v_add_f32_e32 v6, v9, v6
	v_sub_f32_e32 v8, v7, v19
	v_mul_f32_e32 v6, v17, v6
	v_sub_f32_e32 v8, v18, v8
	v_add_f32_e32 v8, v8, v6
	v_add_f32_e32 v10, v7, v8
	v_mul_f32_e32 v11, v10, v10
	v_fmamk_f32 v6, v11, 0x3e9b6dac, v196
	v_fmaak_f32 v133, v11, v6, 0x3f2aaada
	v_cvt_f32_i32_e32 v6, v14
	v_sub_f32_e32 v7, v10, v7
	v_sub_f32_e32 v7, v8, v7
	v_ldexp_f32 v12, v7, 1
	v_mul_f32_e32 v7, v10, v11
	v_ldexp_f32 v9, v10, 1
	v_pk_mul_f32 v[10:11], v[6:7], v[132:133]
	s_nop 0
	v_fma_f32 v8, v6, s66, -v10
	v_fmac_f32_e32 v8, 0xb102e308, v6
	v_pk_add_f32 v[6:7], v[10:11], v[8:9]
	s_nop 0
	v_sub_f32_e32 v9, v7, v9
	v_sub_f32_e32 v9, v11, v9
	v_add_f32_e32 v13, v12, v9
	v_mov_b32_e32 v12, v10
	v_pk_add_f32 v[10:11], v[6:7], v[10:11] neg_lo:[0,1] neg_hi:[0,1]
	v_pk_add_f32 v[14:15], v[6:7], v[12:13]
	v_mov_b32_e32 v9, v6
	v_mov_b32_e32 v11, v15
	v_pk_add_f32 v[16:17], v[8:9], v[10:11] neg_lo:[0,1] neg_hi:[0,1]
	v_pk_add_f32 v[8:9], v[8:9], v[10:11]
	v_mov_b32_e32 v12, v13
	v_pk_add_f32 v[10:11], v[8:9], v[6:7] op_sel:[1,0] op_sel_hi:[0,1] neg_lo:[0,1] neg_hi:[0,1]
	v_pk_add_f32 v[18:19], v[14:15], v[10:11] op_sel_hi:[1,0] neg_lo:[0,1] neg_hi:[0,1]
	v_mov_b32_e32 v14, v15
	v_mov_b32_e32 v15, v9
	v_pk_mov_b32 v[10:11], v[6:7], v[10:11] op_sel:[1,0]
	v_mov_b32_e32 v13, v6
	v_pk_add_f32 v[10:11], v[14:15], v[10:11] neg_lo:[0,1] neg_hi:[0,1]
	v_mov_b32_e32 v18, v16
	v_pk_add_f32 v[6:7], v[12:13], v[10:11] neg_lo:[0,1] neg_hi:[0,1]
	v_mov_b32_e32 v17, v9
	v_pk_add_f32 v[10:11], v[18:19], v[6:7]
	s_nop 0
	v_pk_add_f32 v[12:13], v[10:11], v[10:11] op_sel:[0,1] op_sel_hi:[1,0]
	s_nop 0
	v_pk_add_f32 v[8:9], v[8:9], v[12:13] op_sel:[1,0] op_sel_hi:[0,1]
	v_mov_b32_e32 v11, v8
	v_pk_add_f32 v[14:15], v[10:11], v[16:17] neg_lo:[0,1] neg_hi:[0,1]
	v_mov_b32_e32 v7, v12
	v_sub_f32_e32 v9, v10, v14
	v_pk_add_f32 v[6:7], v[6:7], v[14:15] neg_lo:[0,1] neg_hi:[0,1]
	v_sub_f32_e32 v9, v16, v9
	v_add_f32_e32 v6, v6, v9
	v_add_f32_e32 v6, v6, v7
	v_add_f32_e32 v6, v8, v6
	v_cndmask_b32_e64 v6, v197, v6, s[0:1]
	v_cmp_lt_f32_e64 s[0:1], |v5|, s67
	s_nop 1
	v_cndmask_b32_e64 v5, v6, v5, s[0:1]
	v_sub_f32_e32 v20, v3, v5
	v_add_f32_e32 v6, v3, v5
	v_cndmask_b32_e64 v6, v20, v6, s[82:83]
